# v86 + earlyinv: grid-barrier buffer_inv (L1 invalidate) issued at arrival (before polling / with the leader write-back) instead of after the release
# speedup vs baseline: 1.0136x; 1.0136x over previous
.LBB0_748:
	s_or_b64 exec, exec, s[14:15]
	v_cvt_f32_u32_e32 v6, v4
	s_waitcnt vmcnt(0)
	v_readfirstlane_b32 s7, v5
	v_sub_u32_e32 v5, 0, v4
	v_rcp_iflag_f32_e32 v6, v6
	v_add_u32_e32 v7, s7, v3
	v_mul_f32_e32 v6, 0x4f7ffffe, v6
	v_cvt_u32_f32_e32 v6, v6
	v_mul_lo_u32 v3, v5, v6
	v_mul_hi_u32 v3, v6, v3
	v_add_u32_e32 v3, v6, v3
	v_mul_hi_u32 v3, v7, v3
	v_mul_lo_u32 v5, v3, v4
	v_sub_u32_e32 v5, v7, v5
	v_add_u32_e32 v6, 1, v3
	v_cmp_ge_u32_e32 vcc, v5, v4
	s_nop 1
	v_cndmask_b32_e32 v3, v3, v6, vcc
	v_sub_u32_e32 v6, v5, v4
	v_cndmask_b32_e32 v5, v5, v6, vcc
	v_add_u32_e32 v6, 1, v3
	v_cmp_ge_u32_e32 vcc, v5, v4
	v_add_u32_e32 v5, 1, v7
	s_nop 0
	v_cndmask_b32_e32 v3, v3, v6, vcc
	v_mul_lo_u32 v6, v4, v3
	v_add_u32_e32 v4, v6, v4
	v_cmp_ne_u32_e32 vcc, v5, v4
	s_and_saveexec_b64 s[8:9], vcc
	s_xor_b64 s[14:15], exec, s[8:9]
	s_cbranch_execz .LBB0_762
	buffer_inv sc1
	v_readlane_b32 s8, v255, 6
	v_readlane_b32 s9, v255, 7
	s_waitcnt lgkmcnt(0)
	s_nop 3
	global_load_dword v2, v181, s[8:9] sc1
	s_waitcnt vmcnt(0)
	v_cmp_eq_u32_e32 vcc, v2, v3
	s_and_saveexec_b64 s[18:19], vcc
	s_cbranch_execz .LBB0_761
	s_mov_b32 s7, 1
	s_mov_b64 s[22:23], 0
	s_branch .LBB0_752

.LBB0_761:
	s_or_b64 exec, exec, s[18:19]
	s_waitcnt vmcnt(0)
	s_waitcnt vmcnt(0)
.LBB0_762:
	s_andn2_saveexec_b64 s[8:9], s[14:15]
	s_cbranch_execz .LBB0_782
	s_mov_b64 s[14:15], exec
	buffer_wbl2 sc1
	buffer_inv sc1
	s_waitcnt lgkmcnt(0)
	s_waitcnt vmcnt(0)
	v_mbcnt_lo_u32_b32 v3, s14, 0
	v_mbcnt_hi_u32_b32 v3, s15, v3
	v_cmp_eq_u32_e32 vcc, 0, v3
	s_and_saveexec_b64 s[18:19], vcc
	s_cbranch_execz .LBB0_765
	s_bcnt1_i32_b64 s7, s[14:15]
	v_readlane_b32 s8, v255, 8
	v_mov_b32_e32 v4, s7
	v_readlane_b32 s9, v255, 9
	s_nop 4
	global_atomic_add v4, v181, v4, s[8:9] sc0

.LBB0_779:
	s_or_b64 exec, exec, s[14:15]
	s_mov_b64 s[14:15], exec
	v_mbcnt_lo_u32_b32 v2, s14, 0
	v_mbcnt_hi_u32_b32 v2, s15, v2
	v_cmp_eq_u32_e32 vcc, 0, v2
	s_and_saveexec_b64 s[18:19], vcc
	s_cbranch_execz .LBB0_781
	s_bcnt1_i32_b64 s7, s[14:15]
	v_readlane_b32 s8, v255, 6
	v_mov_b32_e32 v2, s7
	v_readlane_b32 s9, v255, 7
	s_nop 4
	global_atomic_add v181, v2, s[8:9]
.LBB0_781:
	s_or_b64 exec, exec, s[18:19]
	s_waitcnt vmcnt(0)

.LBB0_911:
	s_or_b64 exec, exec, s[14:15]
	s_mov_b64 s[14:15], exec
	v_mbcnt_lo_u32_b32 v2, s14, 0
	v_mbcnt_hi_u32_b32 v2, s15, v2
	v_cmp_eq_u32_e32 vcc, 0, v2
	s_and_saveexec_b64 s[18:19], vcc
	s_cbranch_execz .LBB0_913
	s_bcnt1_i32_b64 s7, s[14:15]
	v_readlane_b32 s8, v255, 6
	v_mov_b32_e32 v2, s7
	v_readlane_b32 s9, v255, 7
	s_nop 4
	global_atomic_add v181, v2, s[8:9]
.LBB0_913:
	s_or_b64 exec, exec, s[18:19]
	s_waitcnt vmcnt(0)

.LBB0_963:
	s_or_b64 exec, exec, s[14:15]
	v_cvt_f32_u32_e32 v6, v4
	s_waitcnt vmcnt(0)
	v_readfirstlane_b32 s6, v5
	v_sub_u32_e32 v5, 0, v4
	v_rcp_iflag_f32_e32 v6, v6
	v_add_u32_e32 v7, s6, v3
	v_mul_f32_e32 v6, 0x4f7ffffe, v6
	v_cvt_u32_f32_e32 v6, v6
	v_mul_lo_u32 v3, v5, v6
	v_mul_hi_u32 v3, v6, v3
	v_add_u32_e32 v3, v6, v3
	v_mul_hi_u32 v3, v7, v3
	v_mul_lo_u32 v5, v3, v4
	v_sub_u32_e32 v5, v7, v5
	v_add_u32_e32 v6, 1, v3
	v_cmp_ge_u32_e32 vcc, v5, v4
	s_nop 1
	v_cndmask_b32_e32 v3, v3, v6, vcc
	v_sub_u32_e32 v6, v5, v4
	v_cndmask_b32_e32 v5, v5, v6, vcc
	v_add_u32_e32 v6, 1, v3
	v_cmp_ge_u32_e32 vcc, v5, v4
	v_add_u32_e32 v5, 1, v7
	s_nop 0
	v_cndmask_b32_e32 v3, v3, v6, vcc
	v_mul_lo_u32 v6, v4, v3
	v_add_u32_e32 v4, v6, v4
	v_cmp_ne_u32_e32 vcc, v5, v4
	s_and_saveexec_b64 s[6:7], vcc
	s_xor_b64 s[14:15], exec, s[6:7]
	s_cbranch_execz .LBB0_977
	buffer_inv sc1
	v_readlane_b32 s6, v255, 6
	v_readlane_b32 s7, v255, 7
	s_waitcnt lgkmcnt(0)
	s_nop 3
	global_load_dword v2, v181, s[6:7] sc1
	s_waitcnt vmcnt(0)
	v_cmp_eq_u32_e32 vcc, v2, v3
	s_and_saveexec_b64 s[18:19], vcc
	s_cbranch_execz .LBB0_976
	s_mov_b32 s6, 1
	s_mov_b64 s[22:23], 0
	s_branch .LBB0_967

.LBB0_977:
	s_andn2_saveexec_b64 s[6:7], s[14:15]
	s_cbranch_execz .LBB0_997
	s_mov_b64 s[14:15], exec
	buffer_wbl2 sc1
	buffer_inv sc1
	s_waitcnt lgkmcnt(0)
	s_waitcnt vmcnt(0)
	v_mbcnt_lo_u32_b32 v3, s14, 0
	v_mbcnt_hi_u32_b32 v3, s15, v3
	v_cmp_eq_u32_e32 vcc, 0, v3
	s_and_saveexec_b64 s[18:19], vcc
	s_cbranch_execz .LBB0_980
	s_bcnt1_i32_b64 s6, s[14:15]
	v_mov_b32_e32 v4, s6
	v_readlane_b32 s6, v255, 8
	v_readlane_b32 s7, v255, 9
	s_nop 4
	global_atomic_add v4, v181, v4, s[6:7] sc0

.LBB0_994:
	s_or_b64 exec, exec, s[14:15]
	s_mov_b64 s[14:15], exec
	v_mbcnt_lo_u32_b32 v2, s14, 0
	v_mbcnt_hi_u32_b32 v2, s15, v2
	v_cmp_eq_u32_e32 vcc, 0, v2
	s_and_saveexec_b64 s[18:19], vcc
	s_cbranch_execz .LBB0_996
	s_bcnt1_i32_b64 s6, s[14:15]
	v_mov_b32_e32 v2, s6
	v_readlane_b32 s6, v255, 6
	v_readlane_b32 s7, v255, 7
	s_nop 4
	global_atomic_add v181, v2, s[6:7]
.LBB0_996:
	s_or_b64 exec, exec, s[18:19]
	s_waitcnt vmcnt(0)

.LBB0_1372:
	s_or_b64 exec, exec, s[18:19]
	v_cvt_f32_u32_e32 v6, v4
	s_waitcnt vmcnt(0)
	v_readfirstlane_b32 s7, v5
	v_sub_u32_e32 v5, 0, v4
	v_rcp_iflag_f32_e32 v6, v6
	v_add_u32_e32 v7, s7, v3
	v_mul_f32_e32 v6, 0x4f7ffffe, v6
	v_cvt_u32_f32_e32 v6, v6
	v_mul_lo_u32 v3, v5, v6
	v_mul_hi_u32 v3, v6, v3
	v_add_u32_e32 v3, v6, v3
	v_mul_hi_u32 v3, v7, v3
	v_mul_lo_u32 v5, v3, v4
	v_sub_u32_e32 v5, v7, v5
	v_add_u32_e32 v6, 1, v3
	v_cmp_ge_u32_e32 vcc, v5, v4
	s_nop 1
	v_cndmask_b32_e32 v3, v3, v6, vcc
	v_sub_u32_e32 v6, v5, v4
	v_cndmask_b32_e32 v5, v5, v6, vcc
	v_add_u32_e32 v6, 1, v3
	v_cmp_ge_u32_e32 vcc, v5, v4
	v_add_u32_e32 v5, 1, v7
	s_nop 0
	v_cndmask_b32_e32 v3, v3, v6, vcc
	v_mul_lo_u32 v6, v4, v3
	v_add_u32_e32 v4, v6, v4
	v_cmp_ne_u32_e32 vcc, v5, v4
	s_and_saveexec_b64 s[8:9], vcc
	s_xor_b64 s[18:19], exec, s[8:9]
	s_cbranch_execz .LBB0_1386
	buffer_inv sc1
	v_readlane_b32 s8, v255, 6
	v_readlane_b32 s9, v255, 7
	s_waitcnt lgkmcnt(0)
	s_nop 3
	global_load_dword v2, v181, s[8:9] sc1
	s_waitcnt vmcnt(0)
	v_cmp_eq_u32_e32 vcc, v2, v3
	s_and_saveexec_b64 s[22:23], vcc
	s_cbranch_execz .LBB0_1385
	s_mov_b32 s7, 1
	s_mov_b64 s[24:25], 0
	s_branch .LBB0_1376

.LBB0_1385:
	s_or_b64 exec, exec, s[22:23]
	s_waitcnt vmcnt(0)
	s_waitcnt vmcnt(0)
.LBB0_1386:
	s_andn2_saveexec_b64 s[8:9], s[18:19]
	s_cbranch_execz .LBB0_1406
	s_mov_b64 s[18:19], exec
	buffer_wbl2 sc1
	buffer_inv sc1
	s_waitcnt lgkmcnt(0)
	s_waitcnt vmcnt(0)
	v_mbcnt_lo_u32_b32 v3, s18, 0
	v_mbcnt_hi_u32_b32 v3, s19, v3
	v_cmp_eq_u32_e32 vcc, 0, v3
	s_and_saveexec_b64 s[22:23], vcc
	s_cbranch_execz .LBB0_1389
	s_bcnt1_i32_b64 s7, s[18:19]
	v_readlane_b32 s8, v255, 8
	v_mov_b32_e32 v4, s7
	v_readlane_b32 s9, v255, 9
	s_nop 4
	global_atomic_add v4, v181, v4, s[8:9] sc0

.LBB0_1403:
	s_or_b64 exec, exec, s[18:19]
	s_mov_b64 s[18:19], exec
	v_mbcnt_lo_u32_b32 v2, s18, 0
	v_mbcnt_hi_u32_b32 v2, s19, v2
	v_cmp_eq_u32_e32 vcc, 0, v2
	s_and_saveexec_b64 s[22:23], vcc
	s_cbranch_execz .LBB0_1405
	s_bcnt1_i32_b64 s7, s[18:19]
	v_readlane_b32 s8, v255, 6
	v_mov_b32_e32 v2, s7
	v_readlane_b32 s9, v255, 7
	s_nop 4
	global_atomic_add v181, v2, s[8:9]
.LBB0_1405:
	s_or_b64 exec, exec, s[22:23]
	s_waitcnt vmcnt(0)

.LBB0_1517:
	s_or_b64 exec, exec, s[10:11]
	v_cvt_f32_u32_e32 v6, v4
	s_waitcnt vmcnt(0)
	v_readfirstlane_b32 s6, v5
	v_sub_u32_e32 v5, 0, v4
	v_rcp_iflag_f32_e32 v6, v6
	v_add_u32_e32 v7, s6, v3
	v_mul_f32_e32 v6, 0x4f7ffffe, v6
	v_cvt_u32_f32_e32 v6, v6
	v_mul_lo_u32 v3, v5, v6
	v_mul_hi_u32 v3, v6, v3
	v_add_u32_e32 v3, v6, v3
	v_mul_hi_u32 v3, v7, v3
	v_mul_lo_u32 v5, v3, v4
	v_sub_u32_e32 v5, v7, v5
	v_add_u32_e32 v6, 1, v3
	v_cmp_ge_u32_e32 vcc, v5, v4
	s_nop 1
	v_cndmask_b32_e32 v3, v3, v6, vcc
	v_sub_u32_e32 v6, v5, v4
	v_cndmask_b32_e32 v5, v5, v6, vcc
	v_add_u32_e32 v6, 1, v3
	v_cmp_ge_u32_e32 vcc, v5, v4
	v_add_u32_e32 v5, 1, v7
	s_nop 0
	v_cndmask_b32_e32 v3, v3, v6, vcc
	v_mul_lo_u32 v6, v4, v3
	v_add_u32_e32 v4, v6, v4
	v_cmp_ne_u32_e32 vcc, v5, v4
	s_and_saveexec_b64 s[6:7], vcc
	s_xor_b64 s[10:11], exec, s[6:7]
	s_cbranch_execz .LBB0_1531
	buffer_inv sc1
	v_readlane_b32 s6, v255, 6
	v_readlane_b32 s7, v255, 7
	s_waitcnt lgkmcnt(0)
	s_nop 3
	global_load_dword v2, v181, s[6:7] sc1
	s_waitcnt vmcnt(0)
	v_cmp_eq_u32_e32 vcc, v2, v3
	s_and_saveexec_b64 s[14:15], vcc
	s_cbranch_execz .LBB0_1530
	s_mov_b32 s6, 1
	s_mov_b64 s[18:19], 0
	s_branch .LBB0_1521

.LBB0_1530:
	s_or_b64 exec, exec, s[14:15]
	s_waitcnt vmcnt(0)
	s_waitcnt vmcnt(0)
.LBB0_1531:
	s_andn2_saveexec_b64 s[6:7], s[10:11]
	s_cbranch_execz .LBB0_1551
	s_mov_b64 s[10:11], exec
	buffer_wbl2 sc1
	buffer_inv sc1
	s_waitcnt lgkmcnt(0)
	s_waitcnt vmcnt(0)
	v_mbcnt_lo_u32_b32 v3, s10, 0
	v_mbcnt_hi_u32_b32 v3, s11, v3
	v_cmp_eq_u32_e32 vcc, 0, v3
	s_and_saveexec_b64 s[14:15], vcc
	s_cbranch_execz .LBB0_1534
	s_bcnt1_i32_b64 s6, s[10:11]
	v_mov_b32_e32 v4, s6
	v_readlane_b32 s6, v255, 8
	v_readlane_b32 s7, v255, 9
	s_nop 4
	global_atomic_add v4, v181, v4, s[6:7] sc0

.LBB0_1548:
	s_or_b64 exec, exec, s[10:11]
	s_mov_b64 s[10:11], exec
	v_mbcnt_lo_u32_b32 v2, s10, 0
	v_mbcnt_hi_u32_b32 v2, s11, v2
	v_cmp_eq_u32_e32 vcc, 0, v2
	s_and_saveexec_b64 s[14:15], vcc
	s_cbranch_execz .LBB0_1550
	s_bcnt1_i32_b64 s6, s[10:11]
	v_mov_b32_e32 v2, s6
	v_readlane_b32 s6, v255, 6
	v_readlane_b32 s7, v255, 7
	s_nop 4
	global_atomic_add v181, v2, s[6:7]
.LBB0_1550:
	s_or_b64 exec, exec, s[14:15]
	s_waitcnt vmcnt(0)

.LBB0_1663:
	s_or_b64 exec, exec, s[14:15]
	s_mov_b64 s[14:15], exec
	v_mbcnt_lo_u32_b32 v2, s14, 0
	v_mbcnt_hi_u32_b32 v2, s15, v2
	v_cmp_eq_u32_e32 vcc, 0, v2
	s_and_saveexec_b64 s[18:19], vcc
	s_cbranch_execz .LBB0_1665
	s_bcnt1_i32_b64 s7, s[14:15]
	v_readlane_b32 s8, v255, 6
	v_mov_b32_e32 v2, s7
	v_readlane_b32 s9, v255, 7
	s_nop 4
	global_atomic_add v181, v2, s[8:9]
.LBB0_1665:
	s_or_b64 exec, exec, s[18:19]
	s_waitcnt vmcnt(0)

.LBB0_2200:
	s_or_b64 exec, exec, s[14:15]
	s_mov_b64 s[14:15], exec
	v_mbcnt_lo_u32_b32 v2, s14, 0
	v_mbcnt_hi_u32_b32 v2, s15, v2
	v_cmp_eq_u32_e32 vcc, 0, v2
	s_and_saveexec_b64 s[18:19], vcc
	s_cbranch_execz .LBB0_2202
	s_bcnt1_i32_b64 s7, s[14:15]
	v_readlane_b32 s8, v255, 6
	v_mov_b32_e32 v2, s7
	v_readlane_b32 s9, v255, 7
	s_nop 4
	global_atomic_add v181, v2, s[8:9]
.LBB0_2202:
	s_or_b64 exec, exec, s[18:19]
	s_waitcnt vmcnt(0)

.LBB0_2380:
	s_or_b64 exec, exec, s[14:15]
	s_mov_b64 s[14:15], exec
	v_mbcnt_lo_u32_b32 v2, s14, 0
	v_mbcnt_hi_u32_b32 v2, s15, v2
	v_cmp_eq_u32_e32 vcc, 0, v2
	s_and_saveexec_b64 s[18:19], vcc
	s_cbranch_execz .LBB0_2382
	s_bcnt1_i32_b64 s6, s[14:15]
	v_mov_b32_e32 v2, s6
	v_readlane_b32 s6, v255, 6
	v_readlane_b32 s7, v255, 7
	s_nop 4
	global_atomic_add v181, v2, s[6:7]
.LBB0_2382:
	s_or_b64 exec, exec, s[18:19]
	s_waitcnt vmcnt(0)
